# M1: vt_item slice loads batched per group; cmp_item weight-fragment loads hoisted per unrolled body with counted waits
# speedup vs baseline: 1.0119x; 1.0023x over previous
.LBB0_659:
	s_add_i32 s19, s34, 0xd80
	s_cmp_gt_u32 s54, 2
	s_cselect_b64 s[38:39], -1, 0
	s_cmp_lt_u32 s54, 3
	s_movk_i32 s10, 0x2040
	s_cselect_b32 s10, s10, 0xd80
	s_add_u32 s36, s34, s10
	s_addc_u32 s37, s35, 0
	s_add_i32 s25, s34, 0xe00
	s_add_i32 s43, s34, 0xe40
	s_add_i32 vcc_lo, s34, 0xe80
	s_add_i32 vcc_hi, s34, 0xec0
	s_cmp_eq_u32 s34, 0
	s_cselect_b64 s[10:11], -1, 0
	s_and_b64 s[40:41], s[10:11], exec
	s_cselect_b32 s68, 0x2040, s19
	v_lshl_add_u64 v[2:3], s[68:69], 1, v[8:9]
	global_load_dwordx4 v[36:39], v[2:3], off
	s_cselect_b32 s68, 0x20c0, s25
	s_mov_b64 s[40:41], -1
	v_lshl_add_u64 v[2:3], s[36:37], 1, v[8:9]
	global_load_dwordx4 v[40:43], v[2:3], off offset:128
	v_lshl_add_u64 v[2:3], s[68:69], 1, v[8:9]
	global_load_dwordx4 v[44:47], v[2:3], off
	s_cselect_b32 s68, 0x21c0, s43
	v_lshl_add_u64 v[2:3], s[68:69], 1, v[8:9]
	global_load_dwordx4 v[48:51], v[2:3], off
	s_cselect_b32 s68, 0x2200, vcc_lo
	v_lshl_add_u64 v[2:3], s[68:69], 1, v[8:9]
	global_load_dwordx4 v[52:55], v[2:3], off
	s_cselect_b32 s68, 0x2240, vcc_hi
	s_cmp_gt_u32 s24, 1
	s_cselect_b64 s[36:37], -1, 0
	s_cmp_lt_u32 s24, 2
	s_cselect_b32 s19, s28, s47
	s_mulk_i32 s19, 0x310
	v_add_u32_e32 v15, s19, v11
	s_cselect_b32 s19, s49, s48
	s_mulk_i32 s19, 0x310
	v_add_u32_e32 v17, s19, v11
	s_cselect_b32 s19, s51, s50
	s_mulk_i32 s19, 0x310
	v_add_u32_e32 v19, s19, v11
	s_cselect_b32 s19, s55, s53
	s_mulk_i32 s19, 0x310
	v_add_u32_e32 v21, s19, v11
	s_cselect_b32 s19, s57, s56
	s_mulk_i32 s19, 0x310
	v_add_u32_e32 v23, s19, v11
	s_cselect_b32 s19, s59, s58
	s_mulk_i32 s19, 0x310
	v_add_u32_e32 v25, s19, v11
	s_cselect_b32 s19, s12, s60
	s_mulk_i32 s19, 0x310
	v_add_u32_e32 v30, s19, v11
	s_cselect_b32 s19, s18, s13
	s_mulk_i32 s19, 0x310
	v_add_u32_e32 v31, s19, v11
	s_and_b64 vcc, exec, s[36:37]
	v_lshl_add_u64 v[2:3], s[68:69], 1, v[8:9]
	global_load_dwordx4 v[56:59], v[2:3], off
	s_waitcnt vmcnt(0)
	ds_write_b128 v13, v[36:39]
	ds_write_b128 v13, v[40:43] offset:128
	ds_write_b128 v13, v[44:47] offset:256
	ds_write_b128 v13, v[48:51] offset:384
	ds_write_b128 v13, v[52:55] offset:512
	ds_write_b128 v13, v[56:59] offset:640
	s_waitcnt lgkmcnt(0)
	s_barrier
	ds_read_u16 v0, v15
	ds_read_u16 v2, v17
	ds_read_u16 v3, v19
	ds_read_u16 v28, v21
	ds_read_u16 v4, v23
	ds_read_u16 v29, v25
	ds_read_u16 v5, v30
	ds_read_u16 v32, v31
	s_waitcnt lgkmcnt(6)
	v_perm_b32 v2, v2, v0, s96
	v_add_u32_e32 v0, s34, v22
	s_waitcnt lgkmcnt(2)
	v_perm_b32 v4, v29, v4, s96
	v_perm_b32 v3, v28, v3, s96
	v_lshlrev_b64 v[28:29], 15, v[0:1]
	v_lshl_add_u64 v[28:29], v[28:29], 0, s[92:93]
	v_cndmask_b32_e64 v29, v29, 0, s[10:11]
	v_cndmask_b32_e64 v28, v28, v10, s[10:11]
	s_waitcnt lgkmcnt(0)
	v_perm_b32 v5, v32, v5, s96
	v_lshl_add_u64 v[28:29], s[66:67], 0, v[28:29]
	s_cbranch_vccz .LBB0_661
	s_lshl_b32 s68, s44, 1
	v_lshl_add_u64 v[32:33], v[28:29], 0, s[68:69]
	s_lshl_b32 s68, s45, 1
	v_lshl_add_u64 v[32:33], v[32:33], 0, s[68:69]
	v_lshl_add_u64 v[32:33], s[26:27], 1, v[32:33]
	global_store_dwordx4 v[32:33], v[2:5], off
	s_mov_b64 s[40:41], 0

.LBB0_795:
	v_lshl_add_u64 v[26:27], v[22:23], 0, s[30:31]
	s_mov_b32 s18, 0x408000
	v_add_co_u32_e32 v24, vcc, s18, v26
	s_mov_b32 s18, 0x418000
	s_nop 0
	v_addc_co_u32_e32 v25, vcc, 0, v27, vcc
	v_add_co_u32_e32 v26, vcc, s18, v26
	s_nop 1
	v_addc_co_u32_e32 v27, vcc, 0, v27, vcc
	global_load_dwordx4 v[70:73], v[24:25], off offset:1024
	global_load_dwordx4 v[74:77], v[26:27], off offset:1024
	global_load_dwordx4 v[78:81], v[24:25], off offset:1088
	global_load_dwordx4 v[82:85], v[26:27], off offset:1088
	global_load_dwordx4 v[86:89], v[24:25], off offset:1152
	global_load_dwordx4 v[90:93], v[26:27], off offset:1152
	global_load_dwordx4 v[94:97], v[24:25], off offset:1216
	global_load_dwordx4 v[98:101], v[26:27], off offset:1216
	global_load_dwordx4 v[102:105], v[24:25], off offset:1280
	global_load_dwordx4 v[106:109], v[26:27], off offset:1280
	global_load_dwordx4 v[110:113], v[24:25], off offset:1344
	global_load_dwordx4 v[114:117], v[26:27], off offset:1344
	global_load_dwordx4 v[118:121], v[24:25], off offset:1408
	global_load_dwordx4 v[122:125], v[26:27], off offset:1408
	global_load_dwordx4 v[126:129], v[24:25], off offset:1472
	global_load_dwordx4 v[130:133], v[26:27], off offset:1472
	s_lshr_b32 s18, s29, 5
	v_add_u32_e32 v28, s18, v29
	s_add_i32 s29, s29, 8
	s_add_i32 s13, s12, -3
	s_and_b32 s13, s13, 12
	v_mad_u64_u32 v[38:39], s[18:19], s13, 34, v[28:29]
	v_mad_u64_u32 v[46:47], s[18:19], v38, s0, v[0:1]
	ds_read_b128 v[38:41], v46
	ds_read_b128 v[42:45], v46 offset:2304
	s_waitcnt vmcnt(14) lgkmcnt(1)
	v_mfma_f32_16x16x32_bf16 v[14:17], v[38:41], v[70:73], v[14:17]
	v_mfma_f32_16x16x32_bf16 v[6:9], v[38:41], v[74:77], v[6:9]
	s_waitcnt lgkmcnt(0)
	v_mfma_f32_16x16x32_bf16 v[10:13], v[42:45], v[70:73], v[10:13]
	v_mfma_f32_16x16x32_bf16 v[2:5], v[42:45], v[74:77], v[2:5]
	ds_read_b128 v[38:41], v46 offset:64
	ds_read_b128 v[42:45], v46 offset:2368
	s_waitcnt vmcnt(12) lgkmcnt(1)
	v_mfma_f32_16x16x32_bf16 v[14:17], v[38:41], v[78:81], v[14:17]
	v_mfma_f32_16x16x32_bf16 v[6:9], v[38:41], v[82:85], v[6:9]
	s_waitcnt lgkmcnt(0)
	v_mfma_f32_16x16x32_bf16 v[10:13], v[42:45], v[78:81], v[10:13]
	v_mfma_f32_16x16x32_bf16 v[2:5], v[42:45], v[82:85], v[2:5]
	s_add_i32 s13, s12, -2
	s_and_b32 s13, s13, 13
	v_mad_u64_u32 v[38:39], s[18:19], s13, 34, v[28:29]
	v_mad_u64_u32 v[46:47], s[18:19], v38, s0, v[0:1]
	ds_read_b128 v[38:41], v46
	ds_read_b128 v[42:45], v46 offset:2304
	s_waitcnt vmcnt(10) lgkmcnt(1)
	v_mfma_f32_16x16x32_bf16 v[14:17], v[38:41], v[86:89], v[14:17]
	v_mfma_f32_16x16x32_bf16 v[6:9], v[38:41], v[90:93], v[6:9]
	s_waitcnt lgkmcnt(0)
	v_mfma_f32_16x16x32_bf16 v[10:13], v[42:45], v[86:89], v[10:13]
	v_mfma_f32_16x16x32_bf16 v[2:5], v[42:45], v[90:93], v[2:5]
	ds_read_b128 v[38:41], v46 offset:64
	ds_read_b128 v[42:45], v46 offset:2368
	s_waitcnt vmcnt(8) lgkmcnt(1)
	v_mfma_f32_16x16x32_bf16 v[14:17], v[38:41], v[94:97], v[14:17]
	v_mfma_f32_16x16x32_bf16 v[6:9], v[38:41], v[98:101], v[6:9]
	s_waitcnt lgkmcnt(0)
	v_mfma_f32_16x16x32_bf16 v[10:13], v[42:45], v[94:97], v[10:13]
	v_mfma_f32_16x16x32_bf16 v[2:5], v[42:45], v[98:101], v[2:5]
	s_add_i32 s13, s12, -1
	s_and_b32 s13, s13, 14
	v_mad_u64_u32 v[38:39], s[18:19], s13, 34, v[28:29]
	v_mad_u64_u32 v[46:47], s[18:19], v38, s0, v[0:1]
	ds_read_b128 v[38:41], v46
	ds_read_b128 v[42:45], v46 offset:2304
	s_waitcnt vmcnt(6) lgkmcnt(1)
	v_mfma_f32_16x16x32_bf16 v[14:17], v[38:41], v[102:105], v[14:17]
	v_mfma_f32_16x16x32_bf16 v[6:9], v[38:41], v[106:109], v[6:9]
	s_waitcnt lgkmcnt(0)
	v_mfma_f32_16x16x32_bf16 v[10:13], v[42:45], v[102:105], v[10:13]
	v_mfma_f32_16x16x32_bf16 v[2:5], v[42:45], v[106:109], v[2:5]
	ds_read_b128 v[38:41], v46 offset:64
	ds_read_b128 v[42:45], v46 offset:2368
	s_waitcnt vmcnt(4) lgkmcnt(1)
	v_mfma_f32_16x16x32_bf16 v[14:17], v[38:41], v[110:113], v[14:17]
	v_mfma_f32_16x16x32_bf16 v[6:9], v[38:41], v[114:117], v[6:9]
	s_waitcnt lgkmcnt(0)
	v_mfma_f32_16x16x32_bf16 v[10:13], v[42:45], v[110:113], v[10:13]
	v_mfma_f32_16x16x32_bf16 v[2:5], v[42:45], v[114:117], v[2:5]
	s_and_b32 s13, s12, 15
	v_mad_u64_u32 v[38:39], s[18:19], s13, 34, v[28:29]
	v_mad_u64_u32 v[46:47], s[18:19], v38, s0, v[0:1]
	ds_read_b128 v[38:41], v46
	ds_read_b128 v[42:45], v46 offset:2304
	s_waitcnt vmcnt(2) lgkmcnt(1)
	v_mfma_f32_16x16x32_bf16 v[14:17], v[38:41], v[118:121], v[14:17]
	v_mfma_f32_16x16x32_bf16 v[6:9], v[38:41], v[122:125], v[6:9]
	s_waitcnt lgkmcnt(0)
	v_mfma_f32_16x16x32_bf16 v[10:13], v[42:45], v[118:121], v[10:13]
	v_mfma_f32_16x16x32_bf16 v[2:5], v[42:45], v[122:125], v[2:5]
	ds_read_b128 v[38:41], v46 offset:64
	ds_read_b128 v[42:45], v46 offset:2368
	s_waitcnt vmcnt(0) lgkmcnt(1)
	v_mfma_f32_16x16x32_bf16 v[14:17], v[38:41], v[126:129], v[14:17]
	v_mfma_f32_16x16x32_bf16 v[6:9], v[38:41], v[130:133], v[6:9]
	s_waitcnt lgkmcnt(0)
	v_mfma_f32_16x16x32_bf16 v[10:13], v[42:45], v[126:129], v[10:13]
	v_mfma_f32_16x16x32_bf16 v[2:5], v[42:45], v[130:133], v[2:5]
	s_add_i32 s12, s12, 4
	s_add_u32 s30, s30, 0x200
	s_addc_u32 s31, s31, 0
	s_cmpk_eq_i32 s30, 0x1000
	s_cbranch_scc0 .LBB0_795
	s_lshl_b32 s4, s4, 11
	s_lshl_b32 s28, s5, 5
	s_ashr_i32 s5, s4, 31
	s_lshl_b64 s[4:5], s[4:5], 2
	s_add_u32 s4, s79, s4
	s_addc_u32 s5, s86, s5
	v_lshl_add_u64 v[24:25], v[20:21], 2, s[4:5]
	global_load_dword v0, v[24:25], off
	global_load_dword v21, v[24:25], off offset:1024
	s_movk_i32 s4, 0x1000
	v_add_co_u32_e32 v22, vcc, s4, v24
	v_readlane_b32 s18, v250, 42
	s_nop 0
	v_addc_co_u32_e32 v23, vcc, 0, v25, vcc
	s_movk_i32 s4, 0x840
	v_lshlrev_b32_e32 v20, 1, v20
	v_lshlrev_b32_e32 v26, 2, v19
	s_waitcnt vmcnt(1)
	v_add_f32_e32 v0, 0, v0
	s_waitcnt vmcnt(0)
	v_add_f32_e32 v0, v0, v21
	global_load_dword v21, v[24:25], off offset:2048
	s_waitcnt vmcnt(0)
	v_add_f32_e32 v0, v0, v21
	global_load_dword v21, v[24:25], off offset:3072
	s_waitcnt vmcnt(0)
	v_add_f32_e32 v0, v0, v21
	global_load_dword v21, v[22:23], off
	s_waitcnt vmcnt(0)
	v_add_f32_e32 v0, v0, v21
	global_load_dword v21, v[22:23], off offset:1024
	s_waitcnt vmcnt(0)
	v_add_f32_e32 v0, v0, v21
	global_load_dword v21, v[22:23], off offset:2048
	s_waitcnt vmcnt(0)
	v_add_f32_e32 v0, v0, v21
	global_load_dword v21, v[22:23], off offset:3072
	s_waitcnt vmcnt(0)
	v_add_f32_e32 v21, v0, v21
	v_add_f32_e32 v0, v14, v21
	v_mul_f32_e32 v14, 0x3d372713, v0
	v_mul_f32_e32 v14, v0, v14
	v_fma_f32 v14, v0, v14, v0
	v_mul_f32_e32 v14, 0x3fcc422a, v14
	v_mul_f32_e32 v14, 0xbfb8aa3b, v14
	v_exp_f32_e32 v14, v14
	v_add_f32_e32 v15, v15, v21
	v_add_f32_e32 v10, v10, v21
	v_add_f32_e32 v14, 1.0, v14
	v_rcp_f32_e32 v14, v14
	s_nop 0
	v_mul_f32_e32 v0, v0, v14
	v_mov_b32_e32 v14, s18
	v_mad_u32_u24 v14, v19, s4, v14
	v_cvt_pk_bf16_f32 v27, v0, s0
	v_add_u32_e32 v28, v14, v20
	ds_write_b16 v28, v27
	v_mul_f32_e32 v27, 0x3d372713, v15
	v_mul_f32_e32 v27, v15, v27
	v_fma_f32 v27, v15, v27, v15
	v_mul_f32_e32 v27, 0x3fcc422a, v27
	v_mul_f32_e32 v27, 0xbfb8aa3b, v27
	v_exp_f32_e32 v27, v27
	v_mul_u32_u24_e32 v0, 0x840, v19
	s_and_b64 s[4:5], s[26:27], exec
	s_mov_b32 s4, 0x2460000
	v_add_f32_e32 v27, 1.0, v27
	v_rcp_f32_e32 v27, v27
	s_cselect_b32 s4, s4, 0x2468000
	s_add_u32 s12, s61, s4
	s_addc_u32 s13, s78, 0
	v_mul_f32_e32 v15, v15, v27
	v_cvt_pk_bf16_f32 v15, v15, s0
	ds_write_b16 v28, v15 offset:528
	v_add_f32_e32 v15, v16, v21
	v_mul_f32_e32 v16, 0x3d372713, v15
	v_mul_f32_e32 v16, v15, v16
	v_fma_f32 v16, v15, v16, v15
	v_mul_f32_e32 v16, 0x3fcc422a, v16
	v_mul_f32_e32 v16, 0xbfb8aa3b, v16
	v_exp_f32_e32 v16, v16
	s_ashr_i32 s5, s35, 4
	s_and_b32 s26, s5, -16
	s_movk_i32 s5, 0x108
	v_add_f32_e32 v16, 1.0, v16
	v_rcp_f32_e32 v16, v16
	s_bfe_u32 s4, s35, 0x20006
	s_and_b64 vcc, exec, s[10:11]
	v_mul_f32_e32 v15, v15, v16
	v_cvt_pk_bf16_f32 v15, v15, s0
	ds_write_b16 v28, v15 offset:1056
	v_add_f32_e32 v15, v17, v21
	v_mul_f32_e32 v16, 0x3d372713, v15
	v_mul_f32_e32 v16, v15, v16
	v_fma_f32 v16, v15, v16, v15
	v_mul_f32_e32 v16, 0x3fcc422a, v16
	v_mul_f32_e32 v16, 0xbfb8aa3b, v16
	v_exp_f32_e32 v16, v16
	s_nop 0
	v_add_f32_e32 v16, 1.0, v16
	v_rcp_f32_e32 v16, v16
	s_nop 0
	v_mul_f32_e32 v15, v15, v16
	v_cvt_pk_bf16_f32 v15, v15, s0
	ds_write_b16 v28, v15 offset:1584
	v_mul_f32_e32 v15, 0x3d372713, v10
	v_mul_f32_e32 v15, v10, v15
	v_fma_f32 v15, v10, v15, v10
	v_mul_f32_e32 v15, 0x3fcc422a, v15
	v_mul_f32_e32 v15, 0xbfb8aa3b, v15
	v_exp_f32_e32 v15, v15
	s_nop 0
	v_add_f32_e32 v15, 1.0, v15
	v_rcp_f32_e32 v15, v15
	s_nop 0
	v_mul_f32_e32 v10, v10, v15
	v_cvt_pk_bf16_f32 v10, v10, s0
	ds_write_b16 v28, v10 offset:8448
	v_add_f32_e32 v10, v11, v21
	v_mul_f32_e32 v11, 0x3d372713, v10
	v_mul_f32_e32 v11, v10, v11
	v_fma_f32 v11, v10, v11, v10
	v_mul_f32_e32 v11, 0x3fcc422a, v11
	v_mul_f32_e32 v11, 0xbfb8aa3b, v11
	v_exp_f32_e32 v11, v11
	s_nop 0
	v_add_f32_e32 v11, 1.0, v11
	v_rcp_f32_e32 v11, v11
	s_nop 0
	v_mul_f32_e32 v10, v10, v11
	v_cvt_pk_bf16_f32 v10, v10, s0
	ds_write_b16 v28, v10 offset:8976
	v_add_f32_e32 v10, v12, v21
	v_mul_f32_e32 v11, 0x3d372713, v10
	v_mul_f32_e32 v11, v10, v11
	v_fma_f32 v11, v10, v11, v10
	v_mul_f32_e32 v11, 0x3fcc422a, v11
	v_mul_f32_e32 v11, 0xbfb8aa3b, v11
	v_exp_f32_e32 v11, v11
	s_nop 0
	v_add_f32_e32 v11, 1.0, v11
	v_rcp_f32_e32 v11, v11
	s_nop 0
	v_mul_f32_e32 v10, v10, v11
	v_cvt_pk_bf16_f32 v10, v10, s0
	ds_write_b16 v28, v10 offset:9504
	v_add_f32_e32 v10, v13, v21
	v_mul_f32_e32 v11, 0x3d372713, v10
	v_mul_f32_e32 v11, v10, v11
	v_fma_f32 v11, v10, v11, v10
	v_mul_f32_e32 v11, 0x3fcc422a, v11
	v_mul_f32_e32 v11, 0xbfb8aa3b, v11
	v_exp_f32_e32 v11, v11
	s_nop 0
	v_add_f32_e32 v11, 1.0, v11
	v_rcp_f32_e32 v11, v11
	s_nop 0
	v_mul_f32_e32 v10, v10, v11
	v_cvt_pk_bf16_f32 v10, v10, s0
	ds_write_b16 v28, v10 offset:10032
	global_load_dword v10, v[24:25], off offset:64
	global_load_dword v11, v[24:25], off offset:1088
	s_waitcnt vmcnt(1)
	v_add_f32_e32 v10, 0, v10
	s_waitcnt vmcnt(0)
	v_add_f32_e32 v10, v10, v11
	global_load_dword v11, v[24:25], off offset:2112
	s_waitcnt vmcnt(0)
	v_add_f32_e32 v10, v10, v11
	global_load_dword v11, v[24:25], off offset:3136
	s_waitcnt vmcnt(0)
	v_add_f32_e32 v10, v10, v11
	global_load_dword v11, v[22:23], off offset:64
	s_waitcnt vmcnt(0)
	v_add_f32_e32 v10, v10, v11
	global_load_dword v11, v[22:23], off offset:1088
	s_waitcnt vmcnt(0)
	v_add_f32_e32 v10, v10, v11
	global_load_dword v11, v[22:23], off offset:2112
	s_waitcnt vmcnt(0)
	v_add_f32_e32 v10, v10, v11
	global_load_dword v11, v[22:23], off offset:3136
	s_waitcnt vmcnt(0)
	v_add_f32_e32 v10, v10, v11
	v_add_f32_e32 v6, v6, v10
	v_mul_f32_e32 v12, 0x3d372713, v6
	v_mul_f32_e32 v12, v6, v12
	v_fma_f32 v12, v6, v12, v6
	v_mul_f32_e32 v12, 0x3fcc422a, v12
	v_mul_f32_e32 v12, 0xbfb8aa3b, v12
	v_exp_f32_e32 v12, v12
	v_or_b32_e32 v11, 32, v20
	v_add3_u32 v0, s18, v11, v0
	v_add_f32_e32 v2, v2, v10
	v_add_f32_e32 v12, 1.0, v12
	v_rcp_f32_e32 v12, v12
	s_nop 0
	v_mul_f32_e32 v6, v6, v12
	v_cvt_pk_bf16_f32 v6, v6, s0
	v_add_u32_e32 v12, v14, v11
	ds_write_b16 v12, v6
	v_add_f32_e32 v6, v7, v10
	v_mul_f32_e32 v7, 0x3d372713, v6
	v_mul_f32_e32 v7, v6, v7
	v_fma_f32 v7, v6, v7, v6
	v_mul_f32_e32 v7, 0x3fcc422a, v7
	v_mul_f32_e32 v7, 0xbfb8aa3b, v7
	v_exp_f32_e32 v7, v7
	s_nop 0
	v_add_f32_e32 v7, 1.0, v7
	v_rcp_f32_e32 v7, v7
	s_nop 0
	v_mul_f32_e32 v6, v6, v7
	v_cvt_pk_bf16_f32 v6, v6, s0
	ds_write_b16 v0, v6 offset:528
	v_add_f32_e32 v6, v8, v10
	v_mul_f32_e32 v7, 0x3d372713, v6
	v_mul_f32_e32 v7, v6, v7
	v_fma_f32 v7, v6, v7, v6
	v_mul_f32_e32 v7, 0x3fcc422a, v7
	v_mul_f32_e32 v7, 0xbfb8aa3b, v7
	v_exp_f32_e32 v7, v7
	s_nop 0
	v_add_f32_e32 v7, 1.0, v7
	v_rcp_f32_e32 v7, v7
	s_nop 0
	v_mul_f32_e32 v6, v6, v7
	v_cvt_pk_bf16_f32 v6, v6, s0
	ds_write_b16 v0, v6 offset:1056
	v_add_f32_e32 v6, v9, v10
	v_mul_f32_e32 v7, 0x3d372713, v6
	v_mul_f32_e32 v7, v6, v7
	v_fma_f32 v7, v6, v7, v6
	v_mul_f32_e32 v7, 0x3fcc422a, v7
	v_mul_f32_e32 v7, 0xbfb8aa3b, v7
	v_exp_f32_e32 v7, v7
	s_nop 0
	v_add_f32_e32 v7, 1.0, v7
	v_rcp_f32_e32 v7, v7
	s_nop 0
	v_mul_f32_e32 v6, v6, v7
	v_cvt_pk_bf16_f32 v6, v6, s0
	ds_write_b16 v0, v6 offset:1584
	v_mul_f32_e32 v6, 0x3d372713, v2
	v_mul_f32_e32 v6, v2, v6
	v_fma_f32 v6, v2, v6, v2
	v_mul_f32_e32 v6, 0x3fcc422a, v6
	v_mul_f32_e32 v6, 0xbfb8aa3b, v6
	v_exp_f32_e32 v6, v6
	s_nop 0
	v_add_f32_e32 v6, 1.0, v6
	v_rcp_f32_e32 v6, v6
	s_nop 0
	v_mul_f32_e32 v2, v2, v6
	v_cvt_pk_bf16_f32 v2, v2, s0
	ds_write_b16 v0, v2 offset:8448
	v_add_f32_e32 v2, v3, v10
	v_mul_f32_e32 v3, 0x3d372713, v2
	v_mul_f32_e32 v3, v2, v3
	v_fma_f32 v3, v2, v3, v2
	v_mul_f32_e32 v3, 0x3fcc422a, v3
	v_mul_f32_e32 v3, 0xbfb8aa3b, v3
	v_exp_f32_e32 v3, v3
	s_nop 0
	v_add_f32_e32 v3, 1.0, v3
	v_rcp_f32_e32 v3, v3
	s_nop 0
	v_mul_f32_e32 v2, v2, v3
	v_cvt_pk_bf16_f32 v2, v2, s0
	ds_write_b16 v0, v2 offset:8976
	v_add_f32_e32 v2, v4, v10
	v_mul_f32_e32 v3, 0x3d372713, v2
	v_mul_f32_e32 v3, v2, v3
	v_fma_f32 v3, v2, v3, v2
	v_mul_f32_e32 v3, 0x3fcc422a, v3
	v_mul_f32_e32 v3, 0xbfb8aa3b, v3
	v_exp_f32_e32 v3, v3
	s_nop 0
	v_add_f32_e32 v3, 1.0, v3
	v_rcp_f32_e32 v3, v3
	s_nop 0
	v_mul_f32_e32 v2, v2, v3
	v_cvt_pk_bf16_f32 v2, v2, s0
	ds_write_b16 v0, v2 offset:9504
	v_add_f32_e32 v2, v5, v10
	v_mul_f32_e32 v3, 0x3d372713, v2
	v_mul_f32_e32 v3, v2, v3
	v_fma_f32 v3, v2, v3, v2
	v_mul_f32_e32 v3, 0x3fcc422a, v3
	v_mul_f32_e32 v3, 0xbfb8aa3b, v3
	v_exp_f32_e32 v3, v3
	s_nop 0
	v_add_f32_e32 v3, 1.0, v3
	v_rcp_f32_e32 v3, v3
	s_nop 0
	v_mul_f32_e32 v2, v2, v3
	v_cvt_pk_bf16_f32 v2, v2, s0
	ds_write_b16 v0, v2 offset:10032
	v_or_b32_e32 v0, s26, v29
	v_mul_lo_u32 v0, v0, s5
	v_lshl_add_u32 v4, v19, 3, v0
	v_lshlrev_b32_e32 v0, 9, v29
	v_lshl_or_b32 v0, s4, 13, v0
	v_lshl_add_u64 v[2:3], s[12:13], 0, v[0:1]
	v_mov_b32_e32 v19, v1
	v_lshl_add_u64 v[14:15], v[2:3], 0, v[18:19]
	s_waitcnt lgkmcnt(0)
	s_barrier
	global_load_dwordx4 v[6:9], v[14:15], off
	global_load_dwordx4 v[10:13], v[14:15], off offset:64
	v_lshl_add_u32 v0, v4, 1, s18
	ds_read_b128 v[2:5], v0
	v_readlane_b32 s12, v250, 53
	v_readlane_b32 s13, v250, 54
	s_mov_b32 s5, s13
	v_writelane_b32 v250, s4, 53
	s_waitcnt vmcnt(1) lgkmcnt(0)
	v_mfma_f32_16x16x32_bf16 v[2:5], v[2:5], v[6:9], 0
	ds_read_b128 v[6:9], v0 offset:64
	v_writelane_b32 v250, s5, 54
	s_waitcnt vmcnt(0) lgkmcnt(0)
	v_mfma_f32_16x16x32_bf16 v[2:5], v[6:9], v[10:13], v[2:5]
	global_load_dwordx4 v[10:13], v[14:15], off offset:128
	ds_read_b128 v[6:9], v0 offset:128
	s_waitcnt vmcnt(0) lgkmcnt(0)
	v_mfma_f32_16x16x32_bf16 v[2:5], v[6:9], v[10:13], v[2:5]
	global_load_dwordx4 v[10:13], v[14:15], off offset:192
	ds_read_b128 v[6:9], v0 offset:192
	s_waitcnt vmcnt(0) lgkmcnt(0)
	v_mfma_f32_16x16x32_bf16 v[2:5], v[6:9], v[10:13], v[2:5]
	global_load_dwordx4 v[10:13], v[14:15], off offset:256
	ds_read_b128 v[6:9], v0 offset:256
	s_waitcnt vmcnt(0) lgkmcnt(0)
	v_mfma_f32_16x16x32_bf16 v[2:5], v[6:9], v[10:13], v[2:5]
	global_load_dwordx4 v[10:13], v[14:15], off offset:320
	ds_read_b128 v[6:9], v0 offset:320
	s_waitcnt vmcnt(0) lgkmcnt(0)
	v_mfma_f32_16x16x32_bf16 v[2:5], v[6:9], v[10:13], v[2:5]
	global_load_dwordx4 v[10:13], v[14:15], off offset:384
	ds_read_b128 v[6:9], v0 offset:384
	s_waitcnt vmcnt(0) lgkmcnt(0)
	v_mfma_f32_16x16x32_bf16 v[2:5], v[6:9], v[10:13], v[2:5]
	global_load_dwordx4 v[10:13], v[14:15], off offset:448
	ds_read_b128 v[6:9], v0 offset:448
	v_mov_b32_e32 v0, s34
	s_mov_b64 s[34:35], -1
	v_readfirstlane_b32 s12, v0
	s_bfe_i64 s[12:13], s[12:13], 0x80000
	s_lshl_b64 s[30:31], s[12:13], 17
	s_waitcnt vmcnt(0) lgkmcnt(0)
	v_mfma_f32_16x16x32_bf16 v[2:5], v[6:9], v[10:13], v[2:5]
	s_cbranch_vccz .LBB0_798
	v_readlane_b32 s5, v249, 42
	s_add_u32 s10, s5, s30
	v_readlane_b32 s5, v249, 43
	v_lshlrev_b32_e32 v0, 11, v29
	s_addc_u32 s11, s5, s31
	v_lshl_or_b32 v0, s4, 15, v0
	v_lshl_add_u64 v[8:9], s[10:11], 0, v[0:1]
	s_ashr_i32 s29, s28, 31
	v_lshl_add_u64 v[8:9], s[28:29], 1, v[8:9]
	s_ashr_i32 s27, s26, 31
	v_lshl_add_u64 v[8:9], s[26:27], 1, v[8:9]
	v_lshlrev_b32_e32 v0, 1, v26
	v_cvt_pk_bf16_f32 v6, v2, v3
	v_cvt_pk_bf16_f32 v7, v4, v5
	v_lshl_add_u64 v[8:9], v[8:9], 0, v[0:1]
	global_store_dwordx2 v[8:9], v[6:7], off
	s_mov_b64 s[34:35], 0
